# previous best plus batched census loads in the first XCD barrier (16 loads issued together instead of one round trip each)
# speedup vs baseline: 1.0048x; 1.0048x over previous
.LBB0_628:
	v_readlane_b32 s36, v252, 29
	s_mov_b64 s[40:41], -1
	s_waitcnt lgkmcnt(0)
	v_readlane_b32 s30, v252, 52
	v_readlane_b32 s31, v252, 53
	s_nop 4
	global_load_dword v0, v97, s[30:31] sc1
	v_readlane_b32 s30, v252, 54
	v_readlane_b32 s31, v252, 55
	s_nop 4
	global_load_dword v1, v97, s[30:31] sc1
	v_readlane_b32 s30, v252, 56
	v_readlane_b32 s31, v252, 57
	s_nop 4
	global_load_dword v2, v97, s[30:31] sc1
	v_readlane_b32 s30, v252, 58
	v_readlane_b32 s31, v252, 59
	s_nop 4
	global_load_dword v3, v97, s[30:31] sc1
	v_readlane_b32 s30, v252, 60
	v_readlane_b32 s31, v252, 61
	s_nop 4
	global_load_dword v4, v97, s[30:31] sc1
	v_readlane_b32 s30, v252, 62
	v_readlane_b32 s31, v252, 63
	s_nop 4
	global_load_dword v5, v97, s[30:31] sc1
	v_readlane_b32 s30, v253, 0
	v_readlane_b32 s31, v253, 1
	s_nop 4
	global_load_dword v6, v97, s[30:31] sc1
	v_readlane_b32 s30, v253, 2
	v_readlane_b32 s31, v253, 3
	s_nop 4
	global_load_dword v7, v97, s[30:31] sc1
	v_readlane_b32 s30, v253, 4
	v_readlane_b32 s31, v253, 5
	s_nop 4
	global_load_dword v8, v97, s[30:31] sc1
	v_readlane_b32 s30, v253, 6
	v_readlane_b32 s31, v253, 7
	s_nop 4
	global_load_dword v9, v97, s[30:31] sc1
	v_readlane_b32 s30, v253, 8
	v_readlane_b32 s31, v253, 9
	s_nop 4
	global_load_dword v10, v97, s[30:31] sc1
	v_readlane_b32 s30, v253, 10
	v_readlane_b32 s31, v253, 11
	s_nop 4
	global_load_dword v11, v97, s[30:31] sc1
	v_readlane_b32 s30, v253, 12
	v_readlane_b32 s31, v253, 13
	s_nop 4
	global_load_dword v12, v97, s[30:31] sc1
	v_readlane_b32 s30, v253, 14
	v_readlane_b32 s31, v253, 15
	s_nop 4
	global_load_dword v13, v97, s[30:31] sc1
	v_readlane_b32 s30, v253, 16
	v_readlane_b32 s31, v253, 17
	s_nop 4
	global_load_dword v14, v97, s[30:31] sc1
	v_readlane_b32 s30, v253, 18
	v_readlane_b32 s31, v253, 19
	s_nop 4
	global_load_dword v15, v97, s[30:31] sc1
	s_mov_b64 s[30:31], -1
	s_waitcnt vmcnt(0)
	v_add_u32_e32 v16, v1, v0
	v_add_u32_e32 v16, v16, v2
	v_add_u32_e32 v16, v16, v3
	v_add_u32_e32 v16, v16, v4
	v_add_u32_e32 v16, v16, v5
	v_add_u32_e32 v16, v16, v6
	v_add_u32_e32 v16, v16, v7
	v_add_u32_e32 v16, v16, v8
	v_add_u32_e32 v16, v16, v9
	v_add_u32_e32 v16, v16, v10
	v_add_u32_e32 v16, v16, v11
	v_add_u32_e32 v16, v16, v12
	v_add_u32_e32 v16, v16, v13
	v_add_u32_e32 v16, v16, v14
	v_add_u32_e32 v16, v16, v15
	v_cmp_eq_u32_e32 vcc, s36, v16
	s_cbranch_vccnz .LBB0_627
	s_and_b32 s30, s24, 0xff
	s_cmp_eq_u32 s30, 0
	s_mov_b64 s[30:31], -1
	s_mov_b64 s[44:45], -1
	s_sleep 1
	s_cbranch_scc0 .LBB0_632
	v_readlane_b32 s30, v252, 50
	v_readlane_b32 s31, v252, 51
	s_nop 4
	global_load_dword v16, v97, s[30:31] sc1
	s_waitcnt vmcnt(0)
	v_cmp_eq_u32_e32 vcc, 0, v16
	s_cbranch_vccnz .LBB0_634
	s_mov_b64 s[44:45], 0
	s_mov_b64 s[30:31], -1
